# sample attention: Q staging block moved between the issue of the K/V cache-row loads and their LDS writes, one memory latency covers both
# speedup vs baseline: 1.0045x; 1.0045x over previous
; #define LAS __attribute__((address_space(3)))
; __device__ __forceinline__ void attn_sample_item(const Params& P, LAS unsigned char* lds, int l, int db, int kvh, int tid_in) {
;     ...
;     const size_t cbase = (size_t)(l * 128 + db) * 128;
; #pragma unroll
;     for (int k = 0; k < 5; ++k) {
;         const int e = tid + 512 * k;
;         if (e < 132 * 16) {
;             const int key = e >> 4, d4 = (e & 15) * 4;
;             f32x4 kv, vv;
;             if (key < 128) { kv = *(const f32x4*)(P.in[I_CK] + ((cbase + key) * 2 + kvh) * 64 + d4); vv = *(const f32x4*)(P.in[I_CV] + ((cbase + key) * 2 + kvh) * 64 + d4); }
;             else { kv = *(const f32x4*)(P.out + O_WKS + ((cbase + key - 4) * 2 + kvh) * 64 + d4); vv = *(const f32x4*)(P.out + O_WVS + ((cbase + key - 4) * 2 + kvh) * 64 + d4); }
;             Ks[key * 65 + d4] = kv[0]; Ks[key * 65 + d4 + 1] = kv[1]; Ks[key * 65 + d4 + 2] = kv[2]; Ks[key * 65 + d4 + 3] = kv[3];
;             *(LAS f32x4*)(Vs + key * 64 + d4) = vv;
;             if (key >= 4 && key < 128) { *(f32x4*)(P.out + O_WKS + ((cbase + key - 4) * 2 + kvh) * 64 + d4) = kv; *(f32x4*)(P.out + O_WVS + ((cbase + key - 4) * 2 + kvh) * 64 + d4) = vv; }
;         }
;     }
.LBB0_954:
	s_cmpk_gt_i32 s14, 0x203
	s_mov_b64 s[0:1], -1
	s_cbranch_scc0 .LBB0_1019
	s_add_i32 s0, s14, 0xfffffdfc
	v_mov_b32_e32 v8, v216
	s_lshr_b32 s16, s0, 1
	s_and_b32 s15, s14, 1
	s_add_i32 s68, s16, s12
	s_lshl_b32 s0, s15, 2
	v_ashrrev_i32_e32 v202, 7, v8
	s_or_b32 s0, s0, s13
	v_add_u32_e32 v202, s0, v202
	v_ashrrev_i32_e32 v203, 31, v202
	v_lshl_add_u64 v[202:203], v[202:203], 2, s[54:55]
	global_load_dword v200, v[202:203], off
	s_movk_i32 s0, 0x840
	v_cmp_gt_i32_e32 vcc, s0, v8
	s_lshl_b32 s4, s68, 7
	v_lshlrev_b32_e32 v11, 2, v8
	v_and_b32_e32 v9, 60, v11
	v_lshlrev_b32_e32 v10, 2, v9
	v_lshrrev_b32_e32 v12, 4, v8
	v_add_u32_e32 v14, s4, v12
	v_lshlrev_b32_e32 v14, 9, v14
	s_lshl_b32 s5, s15, 8
	v_add3_u32 v14, v14, s5, v10
	v_mov_b32_e32 v15, 0
	v_readlane_b32 s40, v252, 29
	v_readlane_b32 s41, v252, 30
	v_readlane_b32 s42, v252, 31
	v_readlane_b32 s43, v252, 32
	v_readlane_b32 s44, v254, 10
	v_readlane_b32 s45, v254, 11
	v_readlane_b32 s46, v254, 14
	v_readlane_b32 s47, v254, 15
	s_mov_b64 s[2:3], 0x4000
	v_readfirstlane_b32 s17, v8
	s_nop 1
	v_lshl_add_u64 v[16:17], s[40:41], 0, v[14:15]
	v_lshl_add_u64 v[26:27], s[42:43], 0, v[14:15]
	global_load_dwordx4 v[48:51], v[16:17], off
	global_load_dwordx4 v[68:71], v[26:27], off
	v_lshl_add_u64 v[18:19], v[16:17], 0, s[2:3]
	v_lshl_add_u64 v[28:29], v[26:27], 0, s[2:3]
	global_load_dwordx4 v[52:55], v[18:19], off
	global_load_dwordx4 v[72:75], v[28:29], off
	v_lshl_add_u64 v[20:21], v[18:19], 0, s[2:3]
	v_lshl_add_u64 v[30:31], v[28:29], 0, s[2:3]
	global_load_dwordx4 v[56:59], v[20:21], off
	global_load_dwordx4 v[76:79], v[30:31], off
	v_lshl_add_u64 v[22:23], v[20:21], 0, s[2:3]
	v_lshl_add_u64 v[32:33], v[30:31], 0, s[2:3]
	global_load_dwordx4 v[60:63], v[22:23], off
	global_load_dwordx4 v[84:87], v[32:33], off
	v_lshl_add_u64 v[16:17], s[44:45], 0, v[14:15]
	v_lshl_add_u64 v[26:27], s[46:47], 0, v[14:15]
	s_cmp_lt_u32 s17, 64
	s_cbranch_scc0 .Lsa_no_k4
	s_mov_b64 s[8:9], 0x10000
	v_lshl_add_u64 v[24:25], v[16:17], 0, s[8:9]
	v_lshl_add_u64 v[34:35], v[26:27], 0, s[8:9]
	global_load_dwordx4 v[64:67], v[24:25], off offset:-2048
	global_load_dwordx4 v[88:91], v[34:35], off offset:-2048
.Lsa_no_k4:
	s_mov_b64 s[0:1], exec

; #define LAS __attribute__((address_space(3)))
; __device__ __forceinline__ void attn_sample_item(const Params& P, LAS unsigned char* lds, int l, int db, int kvh, int tid_in) {
;     ...
;     for (int k = 0; k < 5; ++k) {
;         const int e = tid + 512 * k;
;         if (e < 132 * 16) {
;             const int key = e >> 4, d4 = (e & 15) * 4;
;             f32x4 kv, vv;
;             if (key < 128) { kv = *(const f32x4*)(P.in[I_CK] + ((cbase + key) * 2 + kvh) * 64 + d4); vv = *(const f32x4*)(P.in[I_CV] + ((cbase + key) * 2 + kvh) * 64 + d4); }
;             else { kv = *(const f32x4*)(P.out + O_WKS + ((cbase + key - 4) * 2 + kvh) * 64 + d4); vv = *(const f32x4*)(P.out + O_WVS + ((cbase + key - 4) * 2 + kvh) * 64 + d4); }
;             Ks[key * 65 + d4] = kv[0]; Ks[key * 65 + d4 + 1] = kv[1]; Ks[key * 65 + d4 + 2] = kv[2]; Ks[key * 65 + d4 + 3] = kv[3];
;             *(LAS f32x4*)(Vs + key * 64 + d4) = vv;
;             if (key >= 4 && key < 128) { *(f32x4*)(P.out + O_WKS + ((cbase + key - 4) * 2 + kvh) * 64 + d4) = kv; *(f32x4*)(P.out + O_WVS + ((cbase + key - 4) * 2 + kvh) * 64 + d4) = vv; }
;         }
;     }
.LBB0_1000:
	s_or_b64 exec, exec, s[2:3]
	v_lshlrev_b32_e32 v11, 2, v8
	v_and_b32_e32 v9, 60, v11
	v_lshlrev_b32_e32 v10, 2, v9
	v_lshrrev_b32_e32 v12, 4, v8
	s_lshl_b32 s4, s68, 7
	v_add_u32_e32 v14, s4, v12
	v_lshlrev_b32_e32 v14, 9, v14
	s_lshl_b32 s5, s15, 8
	v_add3_u32 v14, v14, s5, v10
	v_mov_b32_e32 v15, 0
	v_readlane_b32 s44, v254, 10
	v_readlane_b32 s45, v254, 11
	v_readlane_b32 s46, v254, 14
	v_readlane_b32 s47, v254, 15
	s_mov_b64 s[2:3], 0x4000
	v_readfirstlane_b32 s17, v8
	s_nop 1
	v_lshl_add_u64 v[16:17], s[44:45], 0, v[14:15]
	v_lshl_add_u64 v[26:27], s[46:47], 0, v[14:15]
	v_mul_u32_u24_e32 v36, 0x104, v12
	v_add_u32_e32 v36, v36, v10
	v_lshl_add_u32 v37, v12, 8, v10
	v_add_u32_e32 v38, 0x2080, v36
	v_add_u32_e32 v39, 0x4100, v36
	v_add_u32_e32 v13, 0x6180, v36
	s_waitcnt vmcnt(0)
	ds_write2_b32 v36, v48, v49 offset1:1
	ds_write2_b32 v36, v50, v51 offset0:2 offset1:3
	ds_write_b128 v37, v[68:71] offset:34320
	ds_write2_b32 v38, v52, v53 offset1:1
	ds_write2_b32 v38, v54, v55 offset0:2 offset1:3
	ds_write_b128 v37, v[72:75] offset:42512
	ds_write2_b32 v39, v56, v57 offset1:1
	ds_write2_b32 v39, v58, v59 offset0:2 offset1:3
	ds_write_b128 v37, v[76:79] offset:50704
	ds_write2_b32 v13, v60, v61 offset1:1
	ds_write2_b32 v13, v62, v63 offset0:2 offset1:3
	ds_write_b128 v37, v[84:87] offset:58896
	s_cmp_lt_u32 s17, 64
	s_cbranch_scc1 .Lsa_k0_nostore
	global_store_dwordx4 v[16:17], v[48:51], off offset:-2048
	global_store_dwordx4 v[26:27], v[68:71], off offset:-2048

; __device__ __forceinline__ void attn_sample_item(const Params& P, LAS unsigned char* lds, int l, int db, int kvh, int tid_in) {
;     ...
;     __syncthreads();
;     for (int e = tid; e < 16 * 132; e += 512) {
;         const int row = e / 132, key = e % 132, s = row & 3;
;         float acc = 0.f;
; #pragma unroll 16
;         for (int d = 0; d < 64; ++d) acc += qs[row * 64 + d] * Ks[key * 65 + d];
;         const bool ok = key < 128 ? key > s : (key - 128) <= s;
;         S[e] = ok ? acc : -1e30f;
.Lsa_done:
	s_waitcnt lgkmcnt(0)
	s_barrier
	s_and_saveexec_b64 s[2:3], vcc
	s_cbranch_execz .LBB0_1005
	s_mov_b64 s[4:5], 0
	v_mov_b32_e32 v1, v8
